# mlp1 K-loop: in a tile's first iteration after an epilogue the first two counted waits use vmcnt(24) - the previous tile's 16 stores may stay in flight (same loads guaranteed complete)
# speedup vs baseline: 1.0043x; 1.0043x over previous
; #define PG8_STAGE(bufoff, gbase) do { _Pragma("unroll") for (int _i = 0; _i < 2; ++_i) \
;         __builtin_amdgcn_global_load_lds((const unsigned*)((const char*)(gbase) + voffA[_i]), (LAS unsigned*)(lds + (bufoff) + ldsw + _i * 8192), 16, 0, 0); } while (0)
; #define PG8_LDA(dst, b, h) do { _Pragma("unroll") for (int m = 0; m < 4; ++m) _Pragma("unroll") for (int k = 0; k < 2; ++k) dst[m][k] = *(const LAS bf16x8*)(lds + PG8_SA(b, h) + aoff + m * 2048 + k * 1024); } while (0)
; #define PG8_LDB(dst, b, h) do { _Pragma("unroll") for (int n = 0; n < 2; ++n) _Pragma("unroll") for (int k = 0; k < 2; ++k) dst[n][k] = *(const LAS bf16x8*)(lds + PG8_SB(b, h) + boff + n * 2048 + k * 1024); } while (0)
; #define PG8_MMA(ai, bj, At, Bt) do { __builtin_amdgcn_s_setprio(1); _Pragma("unroll") for (int m = 0; m < 4; ++m) _Pragma("unroll") for (int n = 0; n < 2; ++n) _Pragma("unroll") for (int k = 0; k < 2; ++k) \
;         acc[ai][bj][m][n] = __builtin_amdgcn_mfma_f32_16x16x32_bf16(Bt[n][k], At[m][k], acc[ai][bj][m][n], 0, 0, 0); __builtin_amdgcn_s_setprio(0); } while (0)
; #define PG8_WAIT_L(n) asm volatile("s_waitcnt lgkmcnt(" #n ")" ::: "memory")
; #define PG8_BAR __builtin_amdgcn_s_barrier()
; #define PG8_SCHED __builtin_amdgcn_sched_barrier(0)
; template <class Epi>
; DI void gemm_phase(const int TID, const int BID, LAS unsigned char* lds, const Gemm g, const Epi& E) {
;     ...
;         for (int t = 0; t < nt; t += 2) {
;             const bool last = (t == nt - 2);
;             const char* a1 = cA + (size_t)(t + 1) * kstep;
;             const char* a2 = last ? nA : cA + (size_t)(t + 2) * kstep; const char* b2 = last ? nB : cB + (size_t)(t + 2) * kstep;
;             const char* a3 = a2 + kstep; const char* b3 = b2 + kstep;
;             PG8_LDB(B0, 0, 0); PG8_SCHED; PG8_LDA(At, 0, 0); PG8_STAGE(PG8_SA(1, 1), a1 + hstep);
;             PG8_WAIT_L(8); PG8_BAR; PG8_WAIT_L(0); PG8_MMA(0, 0, At, B0); PG8_BAR; PG8_SCHED;
;             PG8_LDB(B1, 0, 1); PG8_STAGE(PG8_SB(0, 0), b2);
;             PG8_BAR; PG8_WAIT_L(0); PG8_MMA(0, 1, At, B1); PG8_BAR;
.LBB0_164:
	v_add_u32_e32 v138, s16, v141
	ds_read_b128 v[134:137], v138
	ds_read_b128 v[144:147], v138 offset:1024
	ds_read_b128 v[148:151], v138 offset:2048
	ds_read_b128 v[152:155], v138 offset:3072
	s_add_i32 s80, s56, 2
	s_add_u32 s58, s54, 0x80
	s_addc_u32 s57, s55, 0
	s_cmp_eq_u32 s62, s56
	s_cselect_b32 s56, s12, s58
	s_cselect_b32 s57, s13, s57
	s_cselect_b32 s59, s53, s77
	s_cselect_b32 s58, s52, s76
	v_lshl_add_u64 v[138:139], s[54:55], 0, v[130:131]
	s_add_i32 m0, s19, 0xc000
	ds_read_b128 v[156:159], v143
	ds_read_b128 v[160:163], v143 offset:1024
	ds_read_b128 v[164:167], v143 offset:2048
	ds_read_b128 v[170:173], v143 offset:3072
	ds_read_b128 v[176:179], v143 offset:4096
	ds_read_b128 v[180:183], v143 offset:5120
	ds_read_b128 v[184:187], v143 offset:6144
	ds_read_b128 v[188:191], v143 offset:7168
	global_load_lds_dwordx4 v[138:139], off
	v_lshl_add_u64 v[138:139], s[54:55], 0, v[132:133]
	s_add_i32 m0, s19, 0xe000
	s_nop 0
	global_load_lds_dwordx4 v[138:139], off
	v_add_u32_e32 v138, s21, v141
	ds_read_b128 v[192:195], v138
	ds_read_b128 v[196:199], v138 offset:1024
	ds_read_b128 v[200:203], v138 offset:2048
	ds_read_b128 v[204:207], v138 offset:3072
	s_cmp_lg_u32 s80, 2
	s_cbranch_scc1 .Lm1w_n1
	s_cmp_lt_u32 s63, 2
	s_cbranch_scc1 .Lm1w_n1
	s_waitcnt vmcnt(24)
	s_branch .Lm1w_j1
.Lm1w_n1:
	s_waitcnt vmcnt(8)
.Lm1w_j1:
	s_waitcnt lgkmcnt(0)
	s_barrier
	s_setprio 1
	v_mfma_f32_16x16x32_bf16 v[124:127], v[134:137], v[156:159], v[124:127]
	v_mfma_f32_16x16x32_bf16 v[120:123], v[148:151], v[156:159], v[120:123]
	v_mfma_f32_16x16x32_bf16 v[108:111], v[134:137], v[164:167], v[108:111]
	v_mfma_f32_16x16x32_bf16 v[104:107], v[148:151], v[164:167], v[104:107]
	v_mfma_f32_16x16x32_bf16 v[92:95], v[134:137], v[176:179], v[92:95]
	v_mfma_f32_16x16x32_bf16 v[88:91], v[148:151], v[176:179], v[88:91]
	v_mfma_f32_16x16x32_bf16 v[76:79], v[134:137], v[184:187], v[76:79]
	v_mfma_f32_16x16x32_bf16 v[72:75], v[148:151], v[184:187], v[72:75]
	v_mfma_f32_16x16x32_bf16 v[124:127], v[144:147], v[160:163], v[124:127]
	v_mfma_f32_16x16x32_bf16 v[120:123], v[152:155], v[160:163], v[120:123]
	v_mfma_f32_16x16x32_bf16 v[108:111], v[144:147], v[170:173], v[108:111]
	v_mfma_f32_16x16x32_bf16 v[104:107], v[152:155], v[170:173], v[104:107]
	v_mfma_f32_16x16x32_bf16 v[92:95], v[144:147], v[180:183], v[92:95]
	v_mfma_f32_16x16x32_bf16 v[88:91], v[152:155], v[180:183], v[88:91]
	v_mfma_f32_16x16x32_bf16 v[76:79], v[144:147], v[188:191], v[76:79]
	v_mfma_f32_16x16x32_bf16 v[72:75], v[152:155], v[188:191], v[72:75]
	v_mfma_f32_16x16x32_bf16 v[116:119], v[192:195], v[156:159], v[116:119]
	v_mfma_f32_16x16x32_bf16 v[112:115], v[200:203], v[156:159], v[112:115]
	v_mfma_f32_16x16x32_bf16 v[100:103], v[192:195], v[164:167], v[100:103]
	v_mfma_f32_16x16x32_bf16 v[96:99], v[200:203], v[164:167], v[96:99]
	v_mfma_f32_16x16x32_bf16 v[84:87], v[192:195], v[176:179], v[84:87]
	v_mfma_f32_16x16x32_bf16 v[80:83], v[200:203], v[176:179], v[80:83]
	v_mfma_f32_16x16x32_bf16 v[68:71], v[192:195], v[184:187], v[68:71]
	v_mfma_f32_16x16x32_bf16 v[64:67], v[200:203], v[184:187], v[64:67]
	v_mfma_f32_16x16x32_bf16 v[116:119], v[196:199], v[160:163], v[116:119]
	v_mfma_f32_16x16x32_bf16 v[112:115], v[204:207], v[160:163], v[112:115]
	v_mfma_f32_16x16x32_bf16 v[100:103], v[196:199], v[170:173], v[100:103]
	v_mfma_f32_16x16x32_bf16 v[96:99], v[204:207], v[170:173], v[96:99]
	v_mfma_f32_16x16x32_bf16 v[84:87], v[196:199], v[180:183], v[84:87]
	v_mfma_f32_16x16x32_bf16 v[80:83], v[204:207], v[180:183], v[80:83]
	v_mfma_f32_16x16x32_bf16 v[68:71], v[196:199], v[188:191], v[68:71]
	v_mfma_f32_16x16x32_bf16 v[64:67], v[204:207], v[188:191], v[64:67]
	s_setprio 0
	s_barrier
	s_mov_b32 m0, s17
	v_lshl_add_u64 v[138:139], s[58:59], 0, v[168:169]
	global_load_lds_dwordx4 v[138:139], off
	v_lshl_add_u64 v[208:209], s[58:59], 0, v[128:129]
	s_mov_b32 m0, s18
	s_nop 0
	global_load_lds_dwordx4 v[208:209], off
	s_mov_b32 m0, s19
	v_lshl_add_u64 v[210:211], s[56:57], 0, v[168:169]
	global_load_lds_dwordx4 v[210:211], off
	v_lshl_add_u64 v[212:213], s[56:57], 0, v[128:129]
	s_mov_b32 m0, s20
	s_nop 0
	global_load_lds_dwordx4 v[212:213], off
	s_add_u32 s58, s58, s0
	s_addc_u32 s59, s59, s1
	s_mov_b32 m0, s22
	v_lshl_add_u64 v[214:215], s[58:59], 0, v[168:169]
	global_load_lds_dwordx4 v[214:215], off
	v_lshl_add_u64 v[216:217], s[58:59], 0, v[128:129]
	s_mov_b32 m0, s23
	s_nop 0
	global_load_lds_dwordx4 v[216:217], off
	ds_read_b128 v[156:159], v143 offset:16384
	ds_read_b128 v[160:163], v143 offset:17408
	ds_read_b128 v[164:167], v143 offset:18432
	ds_read_b128 v[170:173], v143 offset:19456
	ds_read_b128 v[176:179], v143 offset:20480
	ds_read_b128 v[180:183], v143 offset:21504
	ds_read_b128 v[184:187], v143 offset:22528
	ds_read_b128 v[188:191], v143 offset:23552
	s_cmp_lg_u32 s80, 2
	s_cbranch_scc1 .Lm1w_n2
	s_cmp_lt_u32 s63, 2
	s_cbranch_scc1 .Lm1w_n2
	s_waitcnt vmcnt(24)
	s_branch .Lm1w_j2

; #define PG8_STAGE(bufoff, gbase) do { _Pragma("unroll") for (int _i = 0; _i < 2; ++_i) \
;         __builtin_amdgcn_global_load_lds((const unsigned*)((const char*)(gbase) + voffA[_i]), (LAS unsigned*)(lds + (bufoff) + ldsw + _i * 8192), 16, 0, 0); } while (0)
; #define PG8_LDA(dst, b, h) do { _Pragma("unroll") for (int m = 0; m < 4; ++m) _Pragma("unroll") for (int k = 0; k < 2; ++k) dst[m][k] = *(const LAS bf16x8*)(lds + PG8_SA(b, h) + aoff + m * 2048 + k * 1024); } while (0)
; #define PG8_LDB(dst, b, h) do { _Pragma("unroll") for (int n = 0; n < 2; ++n) _Pragma("unroll") for (int k = 0; k < 2; ++k) dst[n][k] = *(const LAS bf16x8*)(lds + PG8_SB(b, h) + boff + n * 2048 + k * 1024); } while (0)
; #define PG8_MMA(ai, bj, At, Bt) do { __builtin_amdgcn_s_setprio(1); _Pragma("unroll") for (int m = 0; m < 4; ++m) _Pragma("unroll") for (int n = 0; n < 2; ++n) _Pragma("unroll") for (int k = 0; k < 2; ++k) \
;         acc[ai][bj][m][n] = __builtin_amdgcn_mfma_f32_16x16x32_bf16(Bt[n][k], At[m][k], acc[ai][bj][m][n], 0, 0, 0); __builtin_amdgcn_s_setprio(0); } while (0)
; #define PG8_WAIT_V(n) asm volatile("s_waitcnt vmcnt(" #n ")" ::: "memory")
; #define PG8_WAIT_L(n) asm volatile("s_waitcnt lgkmcnt(" #n ")" ::: "memory")
; #define PG8_BAR __builtin_amdgcn_s_barrier()
; #define PG8_SCHED __builtin_amdgcn_sched_barrier(0)
; template <class Epi>
; DI void gemm_phase(const int TID, const int BID, LAS unsigned char* lds, const Gemm g, const Epi& E) {
;     ...
;             PG8_BAR; PG8_WAIT_L(0); PG8_MMA(0, 1, At, B1); PG8_BAR;
;             PG8_LDA(At, 0, 1); PG8_STAGE(PG8_SA(0, 0), a2);
;             PG8_BAR; PG8_WAIT_L(0); PG8_MMA(1, 0, At, B0); PG8_BAR; PG8_SCHED;
;             PG8_STAGE(PG8_SB(0, 1), b2 + hstep);
;             PG8_WAIT_V(6); PG8_BAR; PG8_MMA(1, 1, At, B1); PG8_BAR;
;             PG8_LDB(B0, 1, 0); PG8_SCHED; PG8_LDA(At, 1, 0); PG8_STAGE(PG8_SA(0, 1), a2 + hstep);
;             PG8_WAIT_L(8); PG8_BAR; PG8_WAIT_L(0); PG8_MMA(0, 0, At, B0); PG8_BAR; PG8_SCHED;
;             PG8_LDB(B1, 1, 1); PG8_STAGE(PG8_SB(1, 0), b3);
;             PG8_BAR; PG8_WAIT_L(0); PG8_MMA(0, 1, At, B1); PG8_BAR;
.Lm1w_j2:
	s_waitcnt lgkmcnt(0)
	s_barrier
	s_setprio 1
	v_mfma_f32_16x16x32_bf16 v[60:63], v[134:137], v[156:159], v[60:63]
	v_mfma_f32_16x16x32_bf16 v[56:59], v[148:151], v[156:159], v[56:59]
	v_mfma_f32_16x16x32_bf16 v[44:47], v[134:137], v[164:167], v[44:47]
	v_mfma_f32_16x16x32_bf16 v[40:43], v[148:151], v[164:167], v[40:43]
	v_mfma_f32_16x16x32_bf16 v[28:31], v[134:137], v[176:179], v[28:31]
	v_mfma_f32_16x16x32_bf16 v[24:27], v[148:151], v[176:179], v[24:27]
	v_mfma_f32_16x16x32_bf16 v[12:15], v[134:137], v[184:187], v[12:15]
	v_mfma_f32_16x16x32_bf16 v[8:11], v[148:151], v[184:187], v[8:11]
	v_mfma_f32_16x16x32_bf16 v[60:63], v[144:147], v[160:163], v[60:63]
	v_mfma_f32_16x16x32_bf16 v[56:59], v[152:155], v[160:163], v[56:59]
	v_mfma_f32_16x16x32_bf16 v[44:47], v[144:147], v[170:173], v[44:47]
	v_mfma_f32_16x16x32_bf16 v[40:43], v[152:155], v[170:173], v[40:43]
	v_mfma_f32_16x16x32_bf16 v[28:31], v[144:147], v[180:183], v[28:31]
	v_mfma_f32_16x16x32_bf16 v[24:27], v[152:155], v[180:183], v[24:27]
	v_mfma_f32_16x16x32_bf16 v[12:15], v[144:147], v[188:191], v[12:15]
	v_mfma_f32_16x16x32_bf16 v[8:11], v[152:155], v[188:191], v[8:11]
	v_mfma_f32_16x16x32_bf16 v[52:55], v[192:195], v[156:159], v[52:55]
	v_mfma_f32_16x16x32_bf16 v[48:51], v[200:203], v[156:159], v[48:51]
	v_mfma_f32_16x16x32_bf16 v[36:39], v[192:195], v[164:167], v[36:39]
	v_mfma_f32_16x16x32_bf16 v[32:35], v[200:203], v[164:167], v[32:35]
	v_mfma_f32_16x16x32_bf16 v[20:23], v[192:195], v[176:179], v[20:23]
	v_mfma_f32_16x16x32_bf16 v[16:19], v[200:203], v[176:179], v[16:19]
	v_mfma_f32_16x16x32_bf16 v[4:7], v[192:195], v[184:187], v[4:7]
	v_mfma_f32_16x16x32_bf16 v[0:3], v[200:203], v[184:187], v[0:3]
	v_mfma_f32_16x16x32_bf16 v[52:55], v[196:199], v[160:163], v[52:55]
	v_mfma_f32_16x16x32_bf16 v[48:51], v[204:207], v[160:163], v[48:51]
	v_mfma_f32_16x16x32_bf16 v[36:39], v[196:199], v[170:173], v[36:39]
	v_mfma_f32_16x16x32_bf16 v[32:35], v[204:207], v[170:173], v[32:35]
	v_mfma_f32_16x16x32_bf16 v[20:23], v[196:199], v[180:183], v[20:23]
	v_mfma_f32_16x16x32_bf16 v[16:19], v[204:207], v[180:183], v[16:19]
	v_mfma_f32_16x16x32_bf16 v[4:7], v[196:199], v[188:191], v[4:7]
	v_mfma_f32_16x16x32_bf16 v[0:3], v[204:207], v[188:191], v[0:3]
	s_setprio 0
	s_barrier
	s_add_u32 s56, s56, s0
	s_addc_u32 s57, s57, s1
	s_mov_b32 m0, s24
	v_lshl_add_u64 v[192:193], s[56:57], 0, v[168:169]
	global_load_lds_dwordx4 v[192:193], off
	v_lshl_add_u64 v[192:193], s[56:57], 0, v[128:129]
	s_mov_b32 m0, s25
	s_nop 0
	global_load_lds_dwordx4 v[192:193], off
	v_add_u32_e32 v152, s27, v141
	ds_read_b128 v[134:137], v152
	ds_read_b128 v[144:147], v152 offset:1024
	ds_read_b128 v[148:151], v152 offset:2048
	ds_read_b128 v[152:155], v152 offset:3072
	ds_read_b128 v[156:159], v143 offset:32768
	ds_read_b128 v[160:163], v143 offset:33792
	ds_read_b128 v[164:167], v143 offset:34816
	ds_read_b128 v[170:173], v143 offset:35840
	ds_read_b128 v[176:179], v143 offset:36864
	ds_read_b128 v[180:183], v143 offset:37888
	ds_read_b128 v[184:187], v143 offset:38912
	ds_read_b128 v[188:191], v143 offset:39936
	v_add_u32_e32 v175, s33, v141
	ds_read_b128 v[192:195], v175
	ds_read_b128 v[196:199], v175 offset:1024
	ds_read_b128 v[200:203], v175 offset:2048
	ds_read_b128 v[204:207], v175 offset:3072
	s_waitcnt vmcnt(8)
	s_waitcnt lgkmcnt(0)
	s_barrier
	s_setprio 1
	v_mfma_f32_16x16x32_bf16 v[124:127], v[134:137], v[156:159], v[124:127]
	v_mfma_f32_16x16x32_bf16 v[120:123], v[148:151], v[156:159], v[120:123]
	v_mfma_f32_16x16x32_bf16 v[108:111], v[134:137], v[164:167], v[108:111]
	v_mfma_f32_16x16x32_bf16 v[104:107], v[148:151], v[164:167], v[104:107]
	v_mfma_f32_16x16x32_bf16 v[92:95], v[134:137], v[176:179], v[92:95]
	v_mfma_f32_16x16x32_bf16 v[88:91], v[148:151], v[176:179], v[88:91]
	v_mfma_f32_16x16x32_bf16 v[76:79], v[134:137], v[184:187], v[76:79]
	v_mfma_f32_16x16x32_bf16 v[72:75], v[148:151], v[184:187], v[72:75]
	v_mfma_f32_16x16x32_bf16 v[124:127], v[144:147], v[160:163], v[124:127]
	v_mfma_f32_16x16x32_bf16 v[120:123], v[152:155], v[160:163], v[120:123]
	v_mfma_f32_16x16x32_bf16 v[108:111], v[144:147], v[170:173], v[108:111]
	v_mfma_f32_16x16x32_bf16 v[104:107], v[152:155], v[170:173], v[104:107]
	v_mfma_f32_16x16x32_bf16 v[92:95], v[144:147], v[180:183], v[92:95]
	v_mfma_f32_16x16x32_bf16 v[88:91], v[152:155], v[180:183], v[88:91]
	v_mfma_f32_16x16x32_bf16 v[76:79], v[144:147], v[188:191], v[76:79]
	v_mfma_f32_16x16x32_bf16 v[72:75], v[152:155], v[188:191], v[72:75]
	v_mfma_f32_16x16x32_bf16 v[116:119], v[192:195], v[156:159], v[116:119]
	v_mfma_f32_16x16x32_bf16 v[112:115], v[200:203], v[156:159], v[112:115]
	v_mfma_f32_16x16x32_bf16 v[100:103], v[192:195], v[164:167], v[100:103]
	v_mfma_f32_16x16x32_bf16 v[96:99], v[200:203], v[164:167], v[96:99]
	v_mfma_f32_16x16x32_bf16 v[84:87], v[192:195], v[176:179], v[84:87]
	v_mfma_f32_16x16x32_bf16 v[80:83], v[200:203], v[176:179], v[80:83]
	v_mfma_f32_16x16x32_bf16 v[68:71], v[192:195], v[184:187], v[68:71]
	v_mfma_f32_16x16x32_bf16 v[64:67], v[200:203], v[184:187], v[64:67]
	v_mfma_f32_16x16x32_bf16 v[116:119], v[196:199], v[160:163], v[116:119]
	v_mfma_f32_16x16x32_bf16 v[112:115], v[204:207], v[160:163], v[112:115]
	v_mfma_f32_16x16x32_bf16 v[100:103], v[196:199], v[170:173], v[100:103]
	v_mfma_f32_16x16x32_bf16 v[96:99], v[204:207], v[170:173], v[96:99]
	v_mfma_f32_16x16x32_bf16 v[84:87], v[196:199], v[180:183], v[84:87]
	v_mfma_f32_16x16x32_bf16 v[80:83], v[204:207], v[180:183], v[80:83]
	v_mfma_f32_16x16x32_bf16 v[68:71], v[196:199], v[188:191], v[68:71]
	v_mfma_f32_16x16x32_bf16 v[64:67], v[204:207], v[188:191], v[64:67]
	s_setprio 0
	s_barrier
; #define PG8_STAGE(bufoff, gbase) do { _Pragma("unroll") for (int _i = 0; _i < 2; ++_i) \
;         __builtin_amdgcn_global_load_lds((const unsigned*)((const char*)(gbase) + voffA[_i]), (LAS unsigned*)(lds + (bufoff) + ldsw + _i * 8192), 16, 0, 0); } while (0)
; #define PG8_LDA(dst, b, h) do { _Pragma("unroll") for (int m = 0; m < 4; ++m) _Pragma("unroll") for (int k = 0; k < 2; ++k) dst[m][k] = *(const LAS bf16x8*)(lds + PG8_SA(b, h) + aoff + m * 2048 + k * 1024); } while (0)
; #define PG8_MMA(ai, bj, At, Bt) do { __builtin_amdgcn_s_setprio(1); _Pragma("unroll") for (int m = 0; m < 4; ++m) _Pragma("unroll") for (int n = 0; n < 2; ++n) _Pragma("unroll") for (int k = 0; k < 2; ++k) \
;         acc[ai][bj][m][n] = __builtin_amdgcn_mfma_f32_16x16x32_bf16(Bt[n][k], At[m][k], acc[ai][bj][m][n], 0, 0, 0); __builtin_amdgcn_s_setprio(0); } while (0)
; #define PG8_WAIT_V(n) asm volatile("s_waitcnt vmcnt(" #n ")" ::: "memory")
; #define PG8_WAIT_L(n) asm volatile("s_waitcnt lgkmcnt(" #n ")" ::: "memory")
; #define PG8_BAR __builtin_amdgcn_s_barrier()
; #define PG8_SCHED __builtin_amdgcn_sched_barrier(0)
; template <class Epi>
; DI void gemm_phase(const int TID, const int BID, LAS unsigned char* lds, const Gemm g, const Epi& E) {
;     ...
;             PG8_LDA(At, 1, 1); PG8_STAGE(PG8_SA(1, 0), a3);
;             PG8_BAR; PG8_WAIT_L(0); PG8_MMA(1, 0, At, B0); PG8_BAR; PG8_SCHED;
;             PG8_STAGE(PG8_SB(1, 1), b3 + hstep);
;             PG8_WAIT_V(6); PG8_BAR; PG8_MMA(1, 1, At, B1); PG8_BAR;
;         }
	s_mov_b32 m0, s28
	v_lshl_add_u64 v[138:139], v[138:139], 0, s[92:93]
	global_load_lds_dwordx4 v[138:139], off
	v_lshl_add_u64 v[138:139], v[208:209], 0, s[92:93]
	s_mov_b32 m0, s29
	s_nop 0
	global_load_lds_dwordx4 v[138:139], off
	s_mov_b32 m0, s30
	v_lshl_add_u64 v[138:139], v[210:211], 0, s[92:93]
	global_load_lds_dwordx4 v[138:139], off
	v_lshl_add_u64 v[138:139], v[212:213], 0, s[92:93]
	s_mov_b32 m0, s31
	s_nop 0
	global_load_lds_dwordx4 v[138:139], off
	s_mov_b32 m0, s60
	v_lshl_add_u64 v[138:139], v[214:215], 0, s[92:93]
	global_load_lds_dwordx4 v[138:139], off
	v_lshl_add_u64 v[138:139], v[216:217], 0, s[92:93]
	s_mov_b32 m0, s61
	s_nop 0
	global_load_lds_dwordx4 v[138:139], off
	ds_read_b128 v[156:159], v143 offset:49152
	ds_read_b128 v[160:163], v143 offset:50176
	ds_read_b128 v[164:167], v143 offset:51200
	ds_read_b128 v[170:173], v143 offset:52224
	ds_read_b128 v[176:179], v143 offset:53248
	ds_read_b128 v[180:183], v143 offset:54272
	ds_read_b128 v[184:187], v143 offset:55296
	ds_read_b128 v[188:191], v143 offset:56320
	s_waitcnt vmcnt(8)
	s_waitcnt lgkmcnt(0)
	s_barrier
	s_setprio 1
	v_mfma_f32_16x16x32_bf16 v[60:63], v[134:137], v[156:159], v[60:63]
	v_mfma_f32_16x16x32_bf16 v[56:59], v[148:151], v[156:159], v[56:59]
	v_mfma_f32_16x16x32_bf16 v[44:47], v[134:137], v[164:167], v[44:47]
	v_mfma_f32_16x16x32_bf16 v[40:43], v[148:151], v[164:167], v[40:43]
	v_mfma_f32_16x16x32_bf16 v[28:31], v[134:137], v[176:179], v[28:31]
	v_mfma_f32_16x16x32_bf16 v[24:27], v[148:151], v[176:179], v[24:27]
	v_mfma_f32_16x16x32_bf16 v[12:15], v[134:137], v[184:187], v[12:15]
	v_mfma_f32_16x16x32_bf16 v[8:11], v[148:151], v[184:187], v[8:11]
	v_mfma_f32_16x16x32_bf16 v[60:63], v[144:147], v[160:163], v[60:63]
	v_mfma_f32_16x16x32_bf16 v[56:59], v[152:155], v[160:163], v[56:59]
	v_mfma_f32_16x16x32_bf16 v[44:47], v[144:147], v[170:173], v[44:47]
	v_mfma_f32_16x16x32_bf16 v[40:43], v[152:155], v[170:173], v[40:43]
	v_mfma_f32_16x16x32_bf16 v[28:31], v[144:147], v[180:183], v[28:31]
	v_mfma_f32_16x16x32_bf16 v[24:27], v[152:155], v[180:183], v[24:27]
	v_mfma_f32_16x16x32_bf16 v[12:15], v[144:147], v[188:191], v[12:15]
	v_mfma_f32_16x16x32_bf16 v[8:11], v[152:155], v[188:191], v[8:11]
	v_mfma_f32_16x16x32_bf16 v[52:55], v[192:195], v[156:159], v[52:55]
	v_mfma_f32_16x16x32_bf16 v[48:51], v[200:203], v[156:159], v[48:51]
	v_mfma_f32_16x16x32_bf16 v[36:39], v[192:195], v[164:167], v[36:39]
	v_mfma_f32_16x16x32_bf16 v[32:35], v[200:203], v[164:167], v[32:35]
	v_mfma_f32_16x16x32_bf16 v[20:23], v[192:195], v[176:179], v[20:23]
	v_mfma_f32_16x16x32_bf16 v[16:19], v[200:203], v[176:179], v[16:19]
	v_mfma_f32_16x16x32_bf16 v[4:7], v[192:195], v[184:187], v[4:7]
	v_mfma_f32_16x16x32_bf16 v[0:3], v[200:203], v[184:187], v[0:3]
	v_mfma_f32_16x16x32_bf16 v[52:55], v[196:199], v[160:163], v[52:55]
	v_mfma_f32_16x16x32_bf16 v[48:51], v[204:207], v[160:163], v[48:51]
	v_mfma_f32_16x16x32_bf16 v[36:39], v[196:199], v[170:173], v[36:39]
	v_mfma_f32_16x16x32_bf16 v[32:35], v[204:207], v[170:173], v[32:35]
	v_mfma_f32_16x16x32_bf16 v[20:23], v[196:199], v[180:183], v[20:23]
	v_mfma_f32_16x16x32_bf16 v[16:19], v[204:207], v[180:183], v[16:19]
	v_mfma_f32_16x16x32_bf16 v[4:7], v[196:199], v[188:191], v[4:7]
	v_mfma_f32_16x16x32_bf16 v[0:3], v[204:207], v[188:191], v[0:3]
	s_setprio 0
	s_add_u32 s54, s54, 0x100
	s_addc_u32 s55, s55, 0
	s_add_u32 s76, s76, 0x100
	s_addc_u32 s77, s77, 0
	s_cmp_ge_i32 s80, s26
	s_mov_b32 s56, s80
	s_barrier
	s_cbranch_scc0 .LBB0_164
	v_readlane_b32 s76, v255, 9
	v_readlane_b32 s77, v255, 10
	s_branch .LBB0_155
